# grid barrier: non-leader workgroups spin on the global generation word; first barrier reads the 16 arrival counters with all loads in flight
# baseline (speedup 1.0000x reference)
; DI unsigned xb_ld(unsigned* p)              { return __hip_atomic_load(p, __ATOMIC_RELAXED, __HIP_MEMORY_SCOPE_AGENT); }
; DI void xcd_barrier_complete(unsigned* bar, unsigned x, unsigned& nloc, unsigned& nx) {
;   const unsigned G = gridDim.x * gridDim.y * gridDim.z;
;   unsigned sum, cnt, mine, sp = 0u;
;   for (;;) {
;     sum = 0u; cnt = 0u; mine = 0u;
; #pragma unroll
;     for (unsigned j = 0; j < 16; ++j) { const unsigned c = xb_ld(&bar[XB_XCNT(j)]); sum += c; cnt += (c > 0u) ? 1u : 0u; mine = (j == x) ? c : mine; }
;     if (sum == G) break;
;     __builtin_amdgcn_s_sleep(1);
;     if ((++sp & 255u) == 0u) { if (xb_ld(&bar[XB_TMO])) break; if (sp > XB_SPIN_CAP) { atomicAdd(&bar[XB_TMO], 1u); break; } }
;   }
.LBB0_520:
	v_readlane_b32 s20, v254, 38
	s_waitcnt lgkmcnt(0)
	v_readlane_b32 s18, v253, 21
	v_readlane_b32 s19, v253, 22
	s_nop 4
	global_load_dword v0, v1, s[18:19] sc1
	v_readlane_b32 s18, v253, 23
	v_readlane_b32 s19, v253, 24
	s_nop 4
	global_load_dword v2, v1, s[18:19] sc1
	v_readlane_b32 s18, v253, 25
	v_readlane_b32 s19, v253, 26
	s_nop 4
	global_load_dword v3, v1, s[18:19] sc1
	v_readlane_b32 s18, v253, 27
	v_readlane_b32 s19, v253, 28
	s_nop 4
	global_load_dword v4, v1, s[18:19] sc1
	v_readlane_b32 s18, v253, 29
	v_readlane_b32 s19, v253, 30
	s_nop 4
	global_load_dword v5, v1, s[18:19] sc1
	v_readlane_b32 s18, v253, 31
	v_readlane_b32 s19, v253, 32
	s_nop 4
	global_load_dword v6, v1, s[18:19] sc1
	v_readlane_b32 s18, v253, 33
	v_readlane_b32 s19, v253, 34
	s_nop 4
	global_load_dword v7, v1, s[18:19] sc1
	v_readlane_b32 s18, v253, 35
	v_readlane_b32 s19, v253, 36
	s_nop 4
	global_load_dword v8, v1, s[18:19] sc1
	v_readlane_b32 s18, v253, 37
	v_readlane_b32 s19, v253, 38
	s_nop 4
	global_load_dword v9, v1, s[18:19] sc1
	v_readlane_b32 s18, v253, 39
	v_readlane_b32 s19, v253, 40
	s_nop 4
	global_load_dword v10, v1, s[18:19] sc1
	v_readlane_b32 s18, v253, 41
	v_readlane_b32 s19, v253, 42
	s_nop 4
	global_load_dword v11, v1, s[18:19] sc1
	v_readlane_b32 s18, v253, 43
	v_readlane_b32 s19, v253, 44
	s_nop 4
	global_load_dword v12, v1, s[18:19] sc1
	v_readlane_b32 s18, v253, 45
	v_readlane_b32 s19, v253, 46
	s_nop 4
	global_load_dword v13, v1, s[18:19] sc1
	v_readlane_b32 s18, v253, 47
	v_readlane_b32 s19, v253, 48
	s_nop 4
	global_load_dword v14, v1, s[18:19] sc1
	v_readlane_b32 s18, v253, 49
	v_readlane_b32 s19, v253, 50
	s_nop 4
	global_load_dword v15, v1, s[18:19] sc1
	v_readlane_b32 s18, v253, 51
	v_readlane_b32 s19, v253, 52
	s_nop 4
	global_load_dword v16, v1, s[18:19] sc1
	s_mov_b64 s[18:19], -1
	s_waitcnt vmcnt(0)
	v_add_u32_e32 v17, v2, v0
	v_add_u32_e32 v17, v17, v3
	v_add_u32_e32 v17, v17, v4
	v_add_u32_e32 v17, v17, v5
	v_add_u32_e32 v17, v17, v6
	v_add_u32_e32 v17, v17, v7
	v_add_u32_e32 v17, v17, v8
	v_add_u32_e32 v17, v17, v9
	v_add_u32_e32 v17, v17, v10
	v_add_u32_e32 v17, v17, v11
	v_add_u32_e32 v17, v17, v12
	v_add_u32_e32 v17, v17, v13
	v_add_u32_e32 v17, v17, v14
	v_add_u32_e32 v17, v17, v15
	v_add_u32_e32 v17, v17, v16
	v_cmp_eq_u32_e32 vcc, s20, v17
	s_mov_b64 s[20:21], -1
	s_cbranch_vccnz .LBB0_519
	s_and_b32 s18, s2, 0xff
	s_cmp_eq_u32 s18, 0
	s_mov_b64 s[18:19], -1
	s_mov_b64 s[36:37], -1
	s_sleep 1
	s_cbranch_scc1 .LBB0_524
	s_and_b64 vcc, exec, s[36:37]
	s_cbranch_vccz .LBB0_519

; DI unsigned xb_ld(unsigned* p)              { return __hip_atomic_load(p, __ATOMIC_RELAXED, __HIP_MEMORY_SCOPE_AGENT); }
; DI unsigned xb_add(unsigned* p, unsigned v) { return __hip_atomic_fetch_add(p, v, __ATOMIC_RELAXED, __HIP_MEMORY_SCOPE_AGENT); }
; #define XB_SPIN(cond, bar) do { unsigned _sp = 0; while (cond) { __builtin_amdgcn_s_sleep(1); \
;     if ((++_sp & 255u) == 0u) { if (xb_ld(&(bar)[XB_TMO])) break; if (_sp > XB_SPIN_CAP) { atomicAdd(&(bar)[XB_TMO], 1u); break; } } } } while (0)
; DI void xcd_barrier(const XcdBarrier& b) {
;     ...
;     const unsigned old = xb_add(&bar[XB_XSUB(b.x)], 1u);
;     const unsigned gen = old / nloc;
;     if (old + 1u == (gen + 1u) * nloc) {
;       __builtin_amdgcn_fence(__ATOMIC_RELEASE, "agent");
;       asm volatile("s_waitcnt vmcnt(0)" ::: "memory");
;       const unsigned og = xb_add(&bar[XB_TOP], 1u);
;       const unsigned tg = og / nx;
;       if (og + 1u == (tg + 1u) * nx) xb_add(&bar[XB_TOPGEN], 1u);
;       else XB_SPIN(xb_ld(&bar[XB_TOPGEN]) == tg, bar);
;       __builtin_amdgcn_fence(__ATOMIC_ACQUIRE, "agent");
;       xb_add(&bar[XB_XGEN(b.x)], 1u);
;       asm volatile("s_waitcnt vmcnt(0)" ::: "memory");
;     } else {
;       XB_SPIN(xb_ld(&bar[XB_XGEN(b.x)]) == gen, bar);
.LBB0_534:
	s_or_b64 exec, exec, s[18:19]
	v_cvt_f32_u32_e32 v5, v3
	s_waitcnt vmcnt(0)
	v_readfirstlane_b32 s2, v4
	v_sub_u32_e32 v4, 0, v3
	v_rcp_iflag_f32_e32 v5, v5
	v_add_u32_e32 v6, s2, v0
	v_mul_f32_e32 v5, 0x4f7ffffe, v5
	v_cvt_u32_f32_e32 v5, v5
	v_mul_lo_u32 v0, v4, v5
	v_mul_hi_u32 v0, v5, v0
	v_add_u32_e32 v0, v5, v0
	v_mul_hi_u32 v0, v6, v0
	v_mul_lo_u32 v4, v0, v3
	v_sub_u32_e32 v4, v6, v4
	v_add_u32_e32 v5, 1, v0
	v_cmp_ge_u32_e32 vcc, v4, v3
	s_nop 1
	v_cndmask_b32_e32 v0, v0, v5, vcc
	v_sub_u32_e32 v5, v4, v3
	v_cndmask_b32_e32 v4, v4, v5, vcc
	v_add_u32_e32 v5, 1, v0
	v_cmp_ge_u32_e32 vcc, v4, v3
	v_add_u32_e32 v4, 1, v6
	s_nop 0
	v_cndmask_b32_e32 v0, v0, v5, vcc
	v_mul_lo_u32 v5, v3, v0
	v_add_u32_e32 v3, v5, v3
	v_cmp_ne_u32_e32 vcc, v4, v3
	s_and_saveexec_b64 s[18:19], vcc
	s_xor_b64 s[18:19], exec, s[18:19]
	s_cbranch_execz .LBB0_548
	v_readlane_b32 s20, v254, 27
	v_readlane_b32 s21, v254, 28
	s_waitcnt lgkmcnt(0)
	s_nop 3
	global_load_dword v2, v1, s[20:21] sc1
	s_waitcnt vmcnt(0)
	v_cmp_eq_u32_e32 vcc, v2, v0
	s_and_saveexec_b64 s[20:21], vcc
	s_cbranch_execz .LBB0_547
	s_mov_b32 s2, 1
	s_mov_b64 s[36:37], 0
	s_branch .LBB0_538
